# attention online softmax: running-max reference updated once per 64-key iteration (second 32-key block reuses the first block's reference; same math, f32)
# speedup vs baseline: 1.0397x; 1.0014x over previous
; DEV void attn_tile(const Params& p, int l, int tile, char* smem, bool do_store = true) {
;     ...
;     for (int h2 = 0; h2 < 2; ++h2) {
;     const char* kp = Ks + (h2 * 64 + kos) * KROW + (map * 64 + hh * 8) * 2;
;     const char* vp = Vs + ql * KROW + hh * 16 + h2 * 128;
;     bf16x8 kf0[4], kf1[4];
; #pragma unroll
;     for (int ks = 0; ks < 4; ++ks) { kf0[ks] = *(const bf16x8*)(kp + ks * 32); kf1[ks] = *(const bf16x8*)(kp + 32 * KROW + ks * 32); }
;     f32x16 s0, s1;
; #pragma unroll
;     for (int e = 0; e < 16; ++e) { s0[e] = 0.f; s1[e] = 0.f; }
; #pragma unroll
;     for (int ks = 0; ks < 4; ++ks) s0 = __builtin_amdgcn_mfma_f32_32x32x16_bf16(kf0[ks], qf[ks], s0, 0, 0, 0);
; #pragma unroll
;     for (int ks = 0; ks < 4; ++ks) s1 = __builtin_amdgcn_mfma_f32_32x32x16_bf16(kf1[ks], qf[ks], s1, 0, 0, 0);
;     bf16x8 vf[8];
; #pragma unroll
;     for (int dt = 0; dt < 4; ++dt)
; #pragma unroll
;       for (int k2 = 0; k2 < 2; ++k2) vf[dt * 2 + k2] = *(const bf16x8*)(vp + dt * 32 * KROW + (k2 * 16) * 2);
;     float mx = fmaxf(s0[0], s1[0]);
; #pragma unroll
;     for (int e = 1; e < 16; ++e) mx = fmaxf(mx, fmaxf(s0[e], s1[e]));
;     mx = xor32_max(mx);
;     const float mnew = (mx > m + 8.f) ? mx : m;
;     if (__any(mnew > m)) {
;       const float alpha = __builtin_amdgcn_exp2f(m - mnew);
;       lsum *= alpha;
; #pragma unroll
;       for (int dt = 0; dt < 4; ++dt)
; #pragma unroll
;         for (int e = 0; e < 16; ++e) o[dt][e] *= alpha;
;     }
;     m = mnew;
;     bf16x8 pb0[2], pb1[2];
;     {
;       float pe[16];
; #pragma unroll
;       for (int e = 0; e < 16; ++e) { pe[e] = __builtin_amdgcn_exp2f(s0[e] - m); lsum += pe[e]; }
; #pragma unroll
;       for (int k2 = 0; k2 < 2; ++k2) {
;         u32x4 u;
;         u[0] = pk2(pe[8 * k2 + 0], pe[8 * k2 + 1]); u[1] = pk2(pe[8 * k2 + 2], pe[8 * k2 + 3]);
;         u[2] = pk2(pe[8 * k2 + 4], pe[8 * k2 + 5]); u[3] = pk2(pe[8 * k2 + 6], pe[8 * k2 + 7]);
;         pb0[k2] = __builtin_bit_cast(bf16x8, u);
;       }
;     }
; #pragma unroll
;     for (int dt = 0; dt < 4; ++dt)
; #pragma unroll
;       for (int k2 = 0; k2 < 2; ++k2) o[dt] = __builtin_amdgcn_mfma_f32_32x32x16_bf16(vf[dt * 2 + k2], pb0[k2], o[dt], 0, 0, 0);
; #pragma unroll
;     for (int dt = 0; dt < 4; ++dt)
; #pragma unroll
;       for (int k2 = 0; k2 < 2; ++k2) vf[dt * 2 + k2] = *(const bf16x8*)(vp + dt * 32 * KROW + (32 + k2 * 16) * 2);
.LBB0_602:
	v_sub_f32_e32 v80, v80, v211
	v_exp_f32_e32 v178, v80
	v_sub_f32_e32 v80, v81, v211
	v_exp_f32_e32 v179, v80
	v_sub_f32_e32 v80, v82, v211
	v_exp_f32_e32 v180, v80
	v_sub_f32_e32 v80, v83, v211
	v_exp_f32_e32 v181, v80
	v_sub_f32_e32 v80, v84, v211
	v_exp_f32_e32 v208, v80
	v_sub_f32_e32 v80, v85, v211
	v_exp_f32_e32 v212, v80
	v_sub_f32_e32 v80, v86, v211
	v_exp_f32_e32 v213, v80
	v_sub_f32_e32 v80, v87, v211
	v_exp_f32_e32 v214, v80
	v_sub_f32_e32 v80, v88, v211
	v_exp_f32_e32 v88, v80
	v_sub_f32_e32 v80, v89, v211
	v_exp_f32_e32 v89, v80
	v_sub_f32_e32 v80, v90, v211
	v_exp_f32_e32 v90, v80
	v_sub_f32_e32 v80, v91, v211
	v_exp_f32_e32 v91, v80
	v_sub_f32_e32 v80, v92, v211
	v_exp_f32_e32 v92, v80
	v_sub_f32_e32 v80, v93, v211
	v_exp_f32_e32 v93, v80
	v_sub_f32_e32 v80, v94, v211
	v_exp_f32_e32 v94, v80
	v_sub_f32_e32 v80, v95, v211
	v_exp_f32_e32 v215, v80
	v_cvt_pk_bf16_f32 v80, v178, v179
	v_cvt_pk_bf16_f32 v81, v180, v181
	v_cvt_pk_bf16_f32 v82, v208, v212
	v_cvt_pk_bf16_f32 v83, v213, v214
	v_add_f32_e32 v95, v178, v209
	v_add_f32_e32 v95, v179, v95
	s_waitcnt lgkmcnt(5)
	v_mfma_f32_32x32x16_bf16 v[32:47], v[166:169], v[80:83], v[32:47]
	v_add_f32_e32 v95, v180, v95
	v_add_f32_e32 v95, v181, v95
	v_add_f32_e32 v95, v208, v95
	v_add_f32_e32 v95, v212, v95
	v_cvt_pk_bf16_f32 v84, v88, v89
	v_cvt_pk_bf16_f32 v85, v90, v91
	v_cvt_pk_bf16_f32 v86, v92, v93
	v_cvt_pk_bf16_f32 v87, v94, v215
	v_add_f32_e32 v95, v213, v95
	v_mfma_f32_32x32x16_bf16 v[48:63], v[174:177], v[80:83], v[48:63]
	v_sub_f32_e32 v64, v64, v211
	v_add_f32_e32 v95, v214, v95
	v_add_f32_e32 v88, v88, v95
	v_add_f32_e32 v88, v89, v88
	v_add_f32_e32 v88, v90, v88
	v_add_f32_e32 v88, v91, v88
	v_add_f32_e32 v88, v92, v88
	s_waitcnt lgkmcnt(4)
	v_mfma_f32_32x32x16_bf16 v[32:47], v[162:165], v[84:87], v[32:47]
	v_exp_f32_e32 v163, v64
	v_sub_f32_e32 v64, v65, v211
	v_exp_f32_e32 v164, v64
	v_sub_f32_e32 v64, v66, v211
	v_exp_f32_e32 v165, v64
	v_sub_f32_e32 v64, v67, v211
	v_exp_f32_e32 v166, v64
	s_waitcnt lgkmcnt(3)
	v_mfma_f32_32x32x16_bf16 v[16:31], v[146:149], v[80:83], v[16:31]
	v_sub_f32_e32 v64, v68, v211
	v_exp_f32_e32 v167, v64
	v_sub_f32_e32 v64, v69, v211
	v_exp_f32_e32 v168, v64
	v_sub_f32_e32 v64, v70, v211
	v_add_f32_e32 v88, v93, v88
	v_exp_f32_e32 v169, v64
	s_waitcnt lgkmcnt(1)
	v_mfma_f32_32x32x16_bf16 v[0:15], v[154:157], v[80:83], v[0:15]
	v_sub_f32_e32 v64, v71, v211
	v_add_f32_e32 v178, v94, v88
	v_add_f32_e32 v162, v215, v178
	v_add_f32_e32 v162, v163, v162
	v_add_f32_e32 v162, v164, v162
	v_add_f32_e32 v162, v165, v162
	v_add_f32_e32 v162, v166, v162
	v_mfma_f32_32x32x16_bf16 v[48:63], v[170:173], v[84:87], v[48:63]
	v_exp_f32_e32 v170, v64
	v_sub_f32_e32 v64, v72, v211
	v_exp_f32_e32 v72, v64
	v_sub_f32_e32 v64, v73, v211
	v_exp_f32_e32 v73, v64
	v_sub_f32_e32 v64, v74, v211
	v_exp_f32_e32 v74, v64
	v_mfma_f32_32x32x16_bf16 v[16:31], v[150:153], v[84:87], v[16:31]
	v_sub_f32_e32 v64, v75, v211
	v_exp_f32_e32 v75, v64
	v_sub_f32_e32 v64, v76, v211
	v_exp_f32_e32 v76, v64
	v_sub_f32_e32 v64, v77, v211
	v_exp_f32_e32 v77, v64
	v_sub_f32_e32 v64, v78, v211
	s_waitcnt lgkmcnt(0)
	v_mfma_f32_32x32x16_bf16 v[0:15], v[158:161], v[84:87], v[0:15]
	ds_read_b128 v[80:83], v205 offset:34880
	ds_read_b128 v[84:87], v205 offset:34912
	ds_read_b128 v[88:91], v205 offset:43584
	ds_read_b128 v[92:95], v205 offset:43616
	ds_read_b128 v[146:149], v205 offset:52288
	ds_read_b128 v[150:153], v205 offset:52320
	ds_read_b128 v[154:157], v205 offset:60992
	ds_read_b128 v[158:161], v205 offset:61024
	v_add_f32_e32 v162, v167, v162
	v_exp_f32_e32 v78, v64
	v_sub_f32_e32 v64, v79, v211
	v_add_f32_e32 v162, v168, v162
	v_exp_f32_e32 v79, v64
	v_cvt_pk_bf16_f32 v64, v163, v164
	v_cvt_pk_bf16_f32 v65, v165, v166
	v_cvt_pk_bf16_f32 v66, v167, v168
	v_cvt_pk_bf16_f32 v67, v169, v170
	v_add_f32_e32 v162, v169, v162
	v_add_f32_e32 v162, v170, v162
	s_waitcnt lgkmcnt(7)
	v_mfma_f32_32x32x16_bf16 v[48:63], v[80:83], v[64:67], v[48:63]
	v_cvt_pk_bf16_f32 v68, v72, v73
	v_add_f32_e32 v72, v72, v162
	v_add_f32_e32 v72, v73, v72
	v_add_f32_e32 v72, v74, v72
	v_add_f32_e32 v72, v75, v72
	v_add_f32_e32 v72, v76, v72
	v_add_f32_e32 v72, v77, v72
	s_waitcnt lgkmcnt(5)
	v_mfma_f32_32x32x16_bf16 v[32:47], v[88:91], v[64:67], v[32:47]
	v_cvt_pk_bf16_f32 v69, v74, v75
	v_cvt_pk_bf16_f32 v70, v76, v77
	v_cvt_pk_bf16_f32 v71, v78, v79
	v_add_f32_e32 v72, v78, v72
	v_add_f32_e32 v209, v79, v72
	s_waitcnt lgkmcnt(3)
	v_mfma_f32_32x32x16_bf16 v[16:31], v[146:149], v[64:67], v[16:31]
	s_waitcnt lgkmcnt(1)
	v_mfma_f32_32x32x16_bf16 v[0:15], v[154:157], v[64:67], v[0:15]
	v_mfma_f32_32x32x16_bf16 v[48:63], v[84:87], v[68:71], v[48:63]
	v_mfma_f32_32x32x16_bf16 v[32:47], v[92:95], v[68:71], v[32:47]
	v_mfma_f32_32x32x16_bf16 v[16:31], v[150:153], v[68:71], v[16:31]
	s_waitcnt lgkmcnt(0)
	v_mfma_f32_32x32x16_bf16 v[0:15], v[158:161], v[68:71], v[0:15]
	ds_read_b128 v[64:67], v210 offset:26112
	ds_read_b128 v[68:71], v210 offset:17408
	ds_read_b128 v[72:75], v210 offset:17440
	ds_read_b128 v[212:215], v210 offset:26144
	ds_read_b128 v[76:79], v210 offset:17472
	ds_read_b128 v[216:219], v210 offset:26176
	ds_read_b128 v[146:149], v210 offset:17504
	ds_read_b128 v[178:181], v210 offset:26208
	s_waitcnt lgkmcnt(6)
	v_mfma_f32_32x32x16_bf16 v[80:95], v[68:71], v[110:113], 0
	s_waitcnt lgkmcnt(5)
	v_mfma_f32_32x32x16_bf16 v[80:95], v[72:75], v[106:109], v[80:95]
	s_waitcnt lgkmcnt(3)
	v_mfma_f32_32x32x16_bf16 v[80:95], v[76:79], v[102:105], v[80:95]
	v_mfma_f32_32x32x16_bf16 v[64:79], v[64:67], v[110:113], 0
	v_mfma_f32_32x32x16_bf16 v[64:79], v[212:215], v[106:109], v[64:79]
	s_waitcnt lgkmcnt(2)
	v_mfma_f32_32x32x16_bf16 v[64:79], v[216:219], v[102:105], v[64:79]
	s_waitcnt lgkmcnt(1)
	v_mfma_f32_32x32x16_bf16 v[80:95], v[146:149], v[98:101], v[80:95]
	ds_read_b128 v[174:177], v205 offset:34944
	ds_read_b128 v[170:173], v205 offset:34976
	ds_read_b128 v[166:169], v205 offset:43648
	ds_read_b128 v[162:165], v205 offset:43680
	ds_read_b128 v[146:149], v205 offset:52352
	ds_read_b128 v[150:153], v205 offset:52384
	ds_read_b128 v[154:157], v205 offset:61056
	ds_read_b128 v[158:161], v205 offset:61088
	s_waitcnt lgkmcnt(8)
	v_mfma_f32_32x32x16_bf16 v[64:79], v[178:181], v[98:101], v[64:79]
	s_nop 3
	v_mov_b32_e32 v208, v211
	s_branch .LBB0_599
